# attention P.V block runs at raised wave priority (s_setprio 1 around the 16-MFMA block) on top of GEMM hand-off
# speedup vs baseline: 1.0045x; 1.0032x over previous
.LBB0_946:
	s_setprio 1
	s_mul_hi_u32 s6, s81, 0xcccccccd
	s_lshr_b32 s6, s6, 2
	s_mul_i32 s6, s6, 0x14000
	v_subrev_u32_e32 v16, s6, v215
	s_cmp_lg_u32 0, -1
	s_cselect_b32 s6, 0, 0
	v_add_u32_e32 v16, s6, v16
	ds_read_b64_tr_b16 v[116:117], v16 offset:0x1000
	ds_read_b64_tr_b16 v[118:119], v16 offset:0x1800
	ds_read_b64_tr_b16 v[120:121], v16 offset:0x1200
	ds_read_b64_tr_b16 v[122:123], v16 offset:0x1a00
	ds_read_b64_tr_b16 v[124:125], v16 offset:0x1400
	ds_read_b64_tr_b16 v[126:127], v16 offset:0x1c00
	ds_read_b64_tr_b16 v[128:129], v16 offset:0x1600
	ds_read_b64_tr_b16 v[130:131], v16 offset:0x1e00
	s_waitcnt lgkmcnt(8)
	s_nop 0
	v_mfma_f32_32x32x16_bf16 v[66:81], v[228:231], v[180:183], v[66:81]
	v_exp_f32_e32 v132, v132
	v_exp_f32_e32 v133, v133
	v_mfma_f32_32x32x16_bf16 v[50:65], v[232:235], v[180:183], v[50:65]
	v_exp_f32_e32 v134, v134
	v_exp_f32_e32 v135, v135
	v_mfma_f32_32x32x16_bf16 v[34:49], v[236:239], v[180:183], v[34:49]
	v_exp_f32_e32 v136, v136
	v_exp_f32_e32 v137, v137
	v_mfma_f32_32x32x16_bf16 v[18:33], v[240:243], v[180:183], v[18:33]
	v_exp_f32_e32 v138, v138
	v_exp_f32_e32 v139, v139
	ds_read_b64_tr_b16 v[100:101], v16 offset:0x2000
	ds_read_b64_tr_b16 v[102:103], v16 offset:0x2800
	ds_read_b64_tr_b16 v[104:105], v16 offset:0x2200
	ds_read_b64_tr_b16 v[106:107], v16 offset:0x2a00
	ds_read_b64_tr_b16 v[108:109], v16 offset:0x2400
	ds_read_b64_tr_b16 v[110:111], v16 offset:0x2c00
	ds_read_b64_tr_b16 v[112:113], v16 offset:0x2600
	ds_read_b64_tr_b16 v[114:115], v16 offset:0x2e00
	s_waitcnt lgkmcnt(8)
	v_mfma_f32_32x32x16_bf16 v[66:81], v[116:119], v[12:15], v[66:81]
	v_exp_f32_e32 v140, v140
	v_exp_f32_e32 v141, v141
	v_mfma_f32_32x32x16_bf16 v[50:65], v[120:123], v[12:15], v[50:65]
	v_exp_f32_e32 v142, v142
	v_exp_f32_e32 v143, v143
	v_mfma_f32_32x32x16_bf16 v[34:49], v[124:127], v[12:15], v[34:49]
	v_exp_f32_e32 v144, v144
	v_exp_f32_e32 v145, v145
	v_mfma_f32_32x32x16_bf16 v[18:33], v[128:131], v[12:15], v[18:33]
	v_exp_f32_e32 v146, v146
	v_exp_f32_e32 v147, v147
	ds_read_b64_tr_b16 v[12:13], v16 offset:0x3000
	ds_read_b64_tr_b16 v[14:15], v16 offset:0x3800
	ds_read_b64_tr_b16 v[116:117], v16 offset:0x3200
	ds_read_b64_tr_b16 v[118:119], v16 offset:0x3a00
	ds_read_b64_tr_b16 v[120:121], v16 offset:0x3400
	ds_read_b64_tr_b16 v[122:123], v16 offset:0x3c00
	ds_read_b64_tr_b16 v[124:125], v16 offset:0x3600
	ds_read_b64_tr_b16 v[126:127], v16 offset:0x3e00
	s_waitcnt lgkmcnt(8)
	v_mfma_f32_32x32x16_bf16 v[66:81], v[100:103], v[8:11], v[66:81]
	v_exp_f32_e32 v148, v148
	v_exp_f32_e32 v149, v149
	v_mfma_f32_32x32x16_bf16 v[50:65], v[104:107], v[8:11], v[50:65]
	v_exp_f32_e32 v150, v150
	v_exp_f32_e32 v151, v151
	v_mfma_f32_32x32x16_bf16 v[34:49], v[108:111], v[8:11], v[34:49]
	v_exp_f32_e32 v152, v152
	v_exp_f32_e32 v153, v153
	v_mfma_f32_32x32x16_bf16 v[18:33], v[112:115], v[8:11], v[18:33]
	v_exp_f32_e32 v154, v154
	v_exp_f32_e32 v155, v155
	s_waitcnt lgkmcnt(0)
	v_mfma_f32_32x32x16_bf16 v[66:81], v[12:15], v[4:7], v[66:81]
	v_exp_f32_e32 v156, v156
	v_exp_f32_e32 v157, v157
	v_mfma_f32_32x32x16_bf16 v[50:65], v[116:119], v[4:7], v[50:65]
	v_exp_f32_e32 v158, v158
	v_exp_f32_e32 v159, v159
	v_mfma_f32_32x32x16_bf16 v[34:49], v[120:123], v[4:7], v[34:49]
	v_exp_f32_e32 v160, v160
	v_exp_f32_e32 v161, v161
	v_mfma_f32_32x32x16_bf16 v[18:33], v[124:127], v[4:7], v[18:33]
	v_exp_f32_e32 v162, v162
	v_exp_f32_e32 v163, v163
	s_setprio 0

.LBB0_955:
.LBB0_956:
	s_setprio 1
	s_mul_hi_u32 s10, s92, 0xcccccccd
	s_lshr_b32 s10, s10, 2
	v_pk_add_f32 v[184:185], v[16:17], v[16:17] op_sel:[1,0] op_sel_hi:[0,1]
	s_mul_i32 s10, s10, 0x14000
	v_subrev_u32_e32 v3, s10, v214
	s_cmp_lg_u32 0, -1
	s_cselect_b32 s10, 0, 0
	v_add_u32_e32 v3, s10, v3
	ds_read_b64_tr_b16 v[148:149], v3 offset:0x1000
	ds_read_b64_tr_b16 v[150:151], v3 offset:0x1800
	ds_read_b64_tr_b16 v[152:153], v3 offset:0x1200
	ds_read_b64_tr_b16 v[154:155], v3 offset:0x1a00
	ds_read_b64_tr_b16 v[156:157], v3 offset:0x1400
	ds_read_b64_tr_b16 v[158:159], v3 offset:0x1c00
	ds_read_b64_tr_b16 v[160:161], v3 offset:0x1600
	ds_read_b64_tr_b16 v[162:163], v3 offset:0x1e00
	s_waitcnt lgkmcnt(8)
	s_nop 0
	v_mfma_f32_32x32x16_bf16 v[66:81], v[228:231], v[180:183], v[66:81]
	v_exp_f32_e32 v100, v100
	v_exp_f32_e32 v101, v101
	v_mfma_f32_32x32x16_bf16 v[50:65], v[232:235], v[180:183], v[50:65]
	v_exp_f32_e32 v102, v102
	v_exp_f32_e32 v103, v103
	v_mfma_f32_32x32x16_bf16 v[34:49], v[236:239], v[180:183], v[34:49]
	v_exp_f32_e32 v104, v104
	v_exp_f32_e32 v105, v105
	v_mfma_f32_32x32x16_bf16 v[18:33], v[240:243], v[180:183], v[18:33]
	v_exp_f32_e32 v106, v106
	v_exp_f32_e32 v107, v107
	ds_read_b64_tr_b16 v[132:133], v3 offset:0x2000
	ds_read_b64_tr_b16 v[134:135], v3 offset:0x2800
	ds_read_b64_tr_b16 v[136:137], v3 offset:0x2200
	ds_read_b64_tr_b16 v[138:139], v3 offset:0x2a00
	ds_read_b64_tr_b16 v[140:141], v3 offset:0x2400
	ds_read_b64_tr_b16 v[142:143], v3 offset:0x2c00
	ds_read_b64_tr_b16 v[144:145], v3 offset:0x2600
	ds_read_b64_tr_b16 v[146:147], v3 offset:0x2e00
	s_waitcnt lgkmcnt(8)
	v_mfma_f32_32x32x16_bf16 v[66:81], v[148:151], v[12:15], v[66:81]
	v_exp_f32_e32 v108, v108
	v_exp_f32_e32 v109, v109
	v_mfma_f32_32x32x16_bf16 v[50:65], v[152:155], v[12:15], v[50:65]
	v_exp_f32_e32 v110, v110
	v_exp_f32_e32 v111, v111
	v_mfma_f32_32x32x16_bf16 v[34:49], v[156:159], v[12:15], v[34:49]
	v_exp_f32_e32 v112, v112
	v_exp_f32_e32 v113, v113
	v_mfma_f32_32x32x16_bf16 v[18:33], v[160:163], v[12:15], v[18:33]
	v_exp_f32_e32 v114, v114
	v_exp_f32_e32 v115, v115
	ds_read_b64_tr_b16 v[12:13], v3 offset:0x3000
	ds_read_b64_tr_b16 v[14:15], v3 offset:0x3800
	ds_read_b64_tr_b16 v[148:149], v3 offset:0x3200
	ds_read_b64_tr_b16 v[150:151], v3 offset:0x3a00
	ds_read_b64_tr_b16 v[152:153], v3 offset:0x3400
	ds_read_b64_tr_b16 v[154:155], v3 offset:0x3c00
	ds_read_b64_tr_b16 v[156:157], v3 offset:0x3600
	ds_read_b64_tr_b16 v[158:159], v3 offset:0x3e00
	s_waitcnt lgkmcnt(8)
	v_mfma_f32_32x32x16_bf16 v[66:81], v[132:135], v[8:11], v[66:81]
	v_exp_f32_e32 v116, v116
	v_exp_f32_e32 v117, v117
	v_mfma_f32_32x32x16_bf16 v[50:65], v[136:139], v[8:11], v[50:65]
	v_exp_f32_e32 v118, v118
	v_exp_f32_e32 v119, v119
	v_mfma_f32_32x32x16_bf16 v[34:49], v[140:143], v[8:11], v[34:49]
	v_exp_f32_e32 v120, v120
	v_exp_f32_e32 v121, v121
	v_mfma_f32_32x32x16_bf16 v[18:33], v[144:147], v[8:11], v[18:33]
	v_exp_f32_e32 v122, v122
	v_exp_f32_e32 v123, v123
	s_waitcnt lgkmcnt(0)
	v_mfma_f32_32x32x16_bf16 v[66:81], v[12:15], v[4:7], v[66:81]
	v_exp_f32_e32 v124, v124
	v_exp_f32_e32 v125, v125
	v_mfma_f32_32x32x16_bf16 v[50:65], v[148:151], v[4:7], v[50:65]
	v_exp_f32_e32 v126, v126
	v_exp_f32_e32 v127, v127
	v_mfma_f32_32x32x16_bf16 v[34:49], v[152:155], v[4:7], v[34:49]
	v_exp_f32_e32 v128, v128
	v_exp_f32_e32 v129, v129
	v_mfma_f32_32x32x16_bf16 v[18:33], v[156:159], v[4:7], v[18:33]
	v_exp_f32_e32 v130, v130
	v_exp_f32_e32 v131, v131
	s_setprio 0
